# attention PV ds_read2_b64 split to conflict-free ds_read_b64, packed fp32 ops split to scalar; weight-convert tile loads overlapped
# speedup vs baseline: 1.0550x; 1.0122x over previous
.LBB0_74:
	s_abs_i32 s55, s81
	s_mul_hi_u32 s56, s55, s80
	s_mul_i32 s57, s56, s77
	s_sub_i32 s55, s55, s57
	s_ashr_i32 s54, s81, 31
	s_add_i32 s57, s56, 1
	s_sub_i32 s58, s55, s77
	s_cmp_ge_u32 s55, s77
	s_cselect_b32 s56, s57, s56
	s_cselect_b32 s55, s58, s55
	s_add_i32 s57, s56, 1
	s_cmp_ge_u32 s55, s77
	s_cselect_b32 s55, s57, s56
	s_xor_b32 s55, s55, s54
	s_sub_i32 s55, s55, s54
	s_lshl_b32 s54, s55, 6
	s_mul_i32 s55, s55, s77
	s_sub_i32 s55, s81, s55
	s_lshl_b32 s56, s55, 6
	s_ashr_i32 s57, s56, 31
	v_mov_b32_e32 v10, v1
	s_lshl_b64 s[58:59], s[56:57], 2
	s_add_u32 s58, s50, s58
	v_lshlrev_b32_e32 v2, 4, v10
	v_ashrrev_i32_e32 v11, 4, v10
	s_addc_u32 s59, s51, s59
	v_and_b32_e32 v6, 0xf0, v2
	v_mov_b32_e32 v7, v34
	v_lshl_add_u64 v[8:9], s[58:59], 0, v[6:7]
	v_add_u32_e32 v7, s54, v11
	v_mad_u64_u32 v[2:3], s[58:59], v7, s24, 0
	v_ashrrev_i32_e32 v5, 31, v7
	v_mov_b32_e32 v4, v3
	v_mad_u64_u32 v[4:5], s[58:59], v5, s24, v[4:5]
	v_mov_b32_e32 v3, v4
	v_lshl_add_u64 v[2:3], v[2:3], 2, v[8:9]
	global_load_dwordx4 v[2:5], v[2:3], off nt
	v_add_u32_e32 v246, 32, v7
	v_ashrrev_i32_e32 v249, 31, v246
	v_mad_u64_u32 v[246:247], s[58:59], v246, s24, 0
	v_mov_b32_e32 v248, v247
	v_mad_u64_u32 v[248:249], s[58:59], v249, s24, v[248:249]
	v_mov_b32_e32 v247, v248
	v_lshl_add_u64 v[246:247], v[246:247], 2, v[8:9]
	global_load_dwordx4 v[246:249], v[246:247], off nt
	v_mul_lo_u32 v11, v11, s86
	v_add3_u32 v6, 0, v6, v11
	v_ashrrev_i32_e32 v11, 3, v10
	s_ashr_i32 s55, s54, 31
	s_waitcnt vmcnt(1)
	ds_write2_b32 v6, v2, v3 offset1:1
	ds_write2_b32 v6, v4, v5 offset0:2 offset1:3
	v_add_u32_e32 v7, 0x2080, v6
	s_waitcnt vmcnt(0)
	ds_write2_b32 v7, v246, v247 offset1:1
	v_add_u32_e32 v2, 0x2088, v6
	ds_write2_b32 v2, v248, v249 offset1:1
	v_lshlrev_b32_e32 v2, 3, v10
	v_and_b32_e32 v10, 56, v2
	v_lshlrev_b32_e32 v2, 2, v11
	v_mul_u32_u24_e32 v3, 0x104, v10
	v_add3_u32 v6, 0, v2, v3
	s_waitcnt lgkmcnt(0)
	s_barrier
	ds_read2_b32 v[2:3], v6 offset1:65
	ds_read2_b32 v[4:5], v6 offset0:130 offset1:195
	v_add_u32_e32 v8, 0x400, v6
	ds_read2_b32 v[6:7], v8 offset0:4 offset1:69
	ds_read2_b32 v[8:9], v8 offset0:134 offset1:199
	s_waitcnt lgkmcnt(3)
	v_cvt_pk_f16_f32 v2, v2, v3
	s_waitcnt lgkmcnt(2)
	v_cvt_pk_f16_f32 v3, v4, v5
	s_waitcnt lgkmcnt(1)
	v_cvt_pk_f16_f32 v4, v6, v7
	v_add_u32_e32 v6, s56, v11
	s_waitcnt lgkmcnt(0)
	v_cvt_pk_f16_f32 v5, v8, v9
	v_ashrrev_i32_e32 v9, 31, v6
	v_mad_u64_u32 v[6:7], s[56:57], v6, s76, 0
	v_mov_b32_e32 v8, v7
	v_mad_u64_u32 v[8:9], s[56:57], v9, s76, v[8:9]
	v_mov_b32_e32 v7, v8
	v_lshl_add_u64 v[6:7], v[6:7], 1, s[52:53]
	v_lshl_add_u64 v[6:7], s[54:55], 1, v[6:7]
	v_lshlrev_b32_e32 v8, 1, v10
	v_mov_b32_e32 v9, v34
	v_lshl_add_u64 v[6:7], v[6:7], 0, v[8:9]
	global_store_dwordx4 v[6:7], v[2:5], off
	s_barrier
	s_load_dword s54, s[72:73], 0x10
	s_waitcnt lgkmcnt(0)
	s_lshr_b32 s54, s54, 16
	s_cmp_lg_u32 s54, 0
	s_cselect_b64 s[54:55], -1, 0
	s_cmp_lg_u64 s[54:55], 0
	s_addc_u32 s81, s81, s74
	s_cmp_ge_i32 s81, s79
	s_cbranch_scc0 .LBB0_74
	s_branch .LBB0_39

.LBB0_677:
	s_add_i32 s2, s49, -2
	s_and_b32 s50, s2, 1
	v_lshl_add_u32 v10, s50, 14, v176
	v_lshl_add_u32 v145, v157, 4, v10
	v_lshl_add_u32 v144, v175, 4, v10
	ds_read_b128 v[2:5], v145
	ds_read_b128 v[6:9], v145 offset:256
	ds_read_b128 v[10:13], v144 offset:4096
	ds_read_b128 v[14:17], v144 offset:4352
	s_waitcnt lgkmcnt(3)
	v_mfma_f32_16x16x32_f16 v[2:5], v[2:5], v[36:39], 0
	v_cmp_gt_i32_e64 s[40:41], s24, v188
	s_waitcnt lgkmcnt(2)
	v_mfma_f32_16x16x32_f16 v[6:9], v[6:9], v[36:39], 0
	s_waitcnt lgkmcnt(0)
	v_mfma_f32_16x16x32_f16 v[22:25], v[14:17], v[40:43], v[6:9]
	v_mfma_f32_16x16x32_f16 v[18:21], v[10:13], v[40:43], v[2:5]
	s_nop 4
	v_add3_u32 v6, v189, s24, -15
	ds_read_b128 v[2:5], v145 offset:512
	ds_read_b128 v[10:13], v144 offset:4608
	v_max_i32_e32 v14, v6, v167
	ds_read_b128 v[6:9], v145 offset:768
	v_cmp_gt_i32_e32 vcc, s90, v14
	ds_read_b128 v[14:17], v144 offset:4864
	s_waitcnt lgkmcnt(3)
	v_mfma_f32_16x16x32_f16 v[2:5], v[2:5], v[36:39], 0
	s_waitcnt lgkmcnt(2)
	v_mfma_f32_16x16x32_f16 v[26:29], v[10:13], v[40:43], v[2:5]
	v_add_u32_e32 v10, s24, v165
	v_add_u32_e32 v11, 1, v10
	v_add_u32_e32 v12, 2, v10
	s_waitcnt lgkmcnt(1)
	v_mfma_f32_16x16x32_f16 v[2:5], v[6:9], v[36:39], 0
	v_add_u32_e32 v6, 3, v10
	v_add_u32_e32 v7, 16, v10
	v_add_u32_e32 v8, 17, v10
	s_waitcnt lgkmcnt(0)
	v_mfma_f32_16x16x32_f16 v[30:33], v[14:17], v[40:43], v[2:5]
	v_add_u32_e32 v9, 34, v10
	v_add_u32_e32 v13, 35, v10
	v_add_u32_e32 v14, 48, v10
	v_add_u32_e32 v2, 18, v10
	v_add_u32_e32 v3, 19, v10
	v_add_u32_e32 v4, 32, v10
	v_add_u32_e32 v5, 33, v10
	v_add_u32_e32 v15, 49, v10
	v_add_u32_e32 v16, 50, v10
	v_add_u32_e32 v17, 51, v10
	v_med3_i32 v211, v10, s87, v225
	v_med3_i32 v210, v11, s87, v225
	v_med3_i32 v209, v12, s87, v225
	v_med3_i32 v208, v6, s87, v225
	v_med3_i32 v207, v7, s87, v225
	v_med3_i32 v206, v8, s87, v225
	v_med3_i32 v205, v2, s87, v225
	v_med3_i32 v204, v3, s87, v225
	v_med3_i32 v203, v4, s87, v225
	v_med3_i32 v202, v5, s87, v225
	v_med3_i32 v201, v9, s87, v225
	v_med3_i32 v200, v13, s87, v225
	v_med3_i32 v199, v14, s87, v225
	v_med3_i32 v198, v15, s87, v225
	v_med3_i32 v197, v16, s87, v225
	v_med3_i32 v196, v17, s87, v225
	s_and_saveexec_b64 s[2:3], vcc
	s_xor_b64 s[2:3], exec, s[2:3]
	s_cbranch_execz .LBB0_679
	v_lshl_add_u32 v2, v203, 2, s91
	v_lshl_add_u32 v3, v202, 2, s91
	v_lshl_add_u32 v4, v201, 2, s91
	v_lshl_add_u32 v5, v200, 2, s91
	v_lshl_add_u32 v6, v199, 2, s91
	v_lshl_add_u32 v7, v198, 2, s91
	v_lshl_add_u32 v8, v197, 2, s91
	v_lshl_add_u32 v9, v196, 2, s91
	v_lshl_add_u32 v10, v211, 2, s91
	v_lshl_add_u32 v11, v210, 2, s91
	v_lshl_add_u32 v12, v209, 2, s91
	v_lshl_add_u32 v13, v208, 2, s91
	v_lshl_add_u32 v14, v207, 2, s91
	v_lshl_add_u32 v15, v206, 2, s91
	v_lshl_add_u32 v16, v205, 2, s91
	v_lshl_add_u32 v17, v204, 2, s91
	ds_read_b32 v2, v2 offset:512
	ds_read_b32 v3, v3 offset:512
	ds_read_b32 v4, v4 offset:512
	ds_read_b32 v5, v5 offset:512
	ds_read_b32 v6, v6 offset:512
	ds_read_b32 v7, v7 offset:512
	ds_read_b32 v8, v8 offset:512
	ds_read_b32 v9, v9 offset:512
	ds_read_b32 v132, v10 offset:512
	ds_read_b32 v133, v11 offset:512
	ds_read_b32 v134, v12 offset:512
	ds_read_b32 v135, v13 offset:512
	ds_read_b32 v136, v14 offset:512
	ds_read_b32 v137, v15 offset:512
	ds_read_b32 v138, v16 offset:512
	ds_read_b32 v139, v17 offset:512
	s_waitcnt lgkmcnt(8)
	v_fma_f32 v16, v32, s36, v8
	v_fma_f32 v17, v33, s36, v9
	v_fma_f32 v14, v30, s36, v6
	v_fma_f32 v15, v31, s36, v7
	v_fma_f32 v12, v28, s36, v4
	v_fma_f32 v13, v29, s36, v5
	v_fma_f32 v10, v26, s36, v2
	v_fma_f32 v11, v27, s36, v3
	s_waitcnt lgkmcnt(0)
	v_fma_f32 v8, v24, s36, v138
	v_fma_f32 v9, v25, s36, v139
	v_fma_f32 v6, v22, s36, v136
	v_fma_f32 v7, v23, s36, v137
	v_fma_f32 v4, v20, s36, v134
	v_fma_f32 v5, v21, s36, v135
	v_fma_f32 v2, v18, s36, v132
	v_fma_f32 v3, v19, s36, v133
.LBB0_679:
	s_or_saveexec_b64 s[2:3], s[2:3]
	v_cndmask_b32_e64 v132, v186, v187, s[40:41]
	v_mul_f32_e32 v174, 0x3fb8aa3b, v132
	s_xor_b64 exec, exec, s[2:3]
	v_fma_f32 v16, v32, s36, v174
	v_fma_f32 v17, v33, s36, v174
	v_fma_f32 v12, v28, s36, v174
	v_fma_f32 v13, v29, s36, v174
	v_fma_f32 v8, v24, s36, v174
	v_fma_f32 v9, v25, s36, v174
	v_fma_f32 v4, v20, s36, v174
	v_fma_f32 v5, v21, s36, v174
	v_fma_f32 v14, v30, s36, v174
	v_fma_f32 v15, v31, s36, v174
	v_fma_f32 v10, v26, s36, v174
	v_fma_f32 v11, v27, s36, v174
	v_fma_f32 v6, v22, s36, v174
	v_fma_f32 v7, v23, s36, v174
	v_fma_f32 v2, v18, s36, v174
	v_fma_f32 v3, v19, s36, v174
	s_or_b64 exec, exec, s[2:3]
	v_max_f32_e32 v18, v3, v3
	v_max_f32_e32 v19, v2, v2
	v_max_f32_e32 v18, v19, v18
	v_max3_f32 v18, v18, v4, v5
	v_max3_f32 v18, v18, v6, v7
	v_max3_f32 v18, v18, v8, v9
	v_max3_f32 v18, v18, v10, v11
	v_max3_f32 v18, v18, v12, v13
	v_max3_f32 v18, v18, v14, v15
	v_max3_f32 v18, v18, v16, v17
	ds_bpermute_b32 v19, v35, v18
	s_waitcnt lgkmcnt(0)
	v_max_f32_e32 v19, v19, v19
	v_max_f32_e32 v194, v18, v19
	ds_bpermute_b32 v195, v149, v194
	ds_read_b128 v[18:21], v145 offset:8192
	ds_read_b128 v[22:25], v144 offset:12288
	s_waitcnt lgkmcnt(1)
	v_mfma_f32_16x16x32_f16 v[18:21], v[18:21], v[44:47], 0
	s_waitcnt lgkmcnt(0)
	v_mfma_f32_16x16x32_f16 v[132:135], v[22:25], v[48:51], v[18:21]
	ds_read_b128 v[22:25], v144 offset:12544
	s_nop 4
	ds_read_b128 v[18:21], v145 offset:8448
	s_waitcnt lgkmcnt(0)
	v_mfma_f32_16x16x32_f16 v[18:21], v[18:21], v[44:47], 0
	v_mfma_f32_16x16x32_f16 v[136:139], v[22:25], v[48:51], v[18:21]
	ds_read_b128 v[22:25], v144 offset:12800
	s_nop 5
	ds_read_b128 v[18:21], v145 offset:8704
	s_waitcnt lgkmcnt(0)
	v_mfma_f32_16x16x32_f16 v[18:21], v[18:21], v[44:47], 0
	v_mfma_f32_16x16x32_f16 v[140:143], v[22:25], v[48:51], v[18:21]
	ds_read_b128 v[22:25], v144 offset:13056
	s_nop 5
	ds_read_b128 v[18:21], v145 offset:8960
	s_waitcnt lgkmcnt(0)
	v_mfma_f32_16x16x32_f16 v[18:21], v[18:21], v[44:47], 0
	v_mfma_f32_16x16x32_f16 v[144:147], v[22:25], v[48:51], v[18:21]
	s_and_saveexec_b64 s[2:3], vcc
	s_xor_b64 s[2:3], exec, s[2:3]
	s_cbranch_execz .LBB0_683
	s_nop 3
	v_lshl_add_u32 v18, v203, 2, s91
	v_lshl_add_u32 v19, v202, 2, s91
	v_lshl_add_u32 v20, v201, 2, s91
	v_lshl_add_u32 v21, v200, 2, s91
	v_lshl_add_u32 v22, v199, 2, s91
	v_lshl_add_u32 v23, v198, 2, s91
	v_lshl_add_u32 v24, v197, 2, s91
	v_lshl_add_u32 v25, v196, 2, s91
	v_lshl_add_u32 v26, v211, 2, s91
	v_lshl_add_u32 v27, v210, 2, s91
	v_lshl_add_u32 v28, v209, 2, s91
	v_lshl_add_u32 v29, v208, 2, s91
	v_lshl_add_u32 v30, v207, 2, s91
	v_lshl_add_u32 v31, v206, 2, s91
	v_lshl_add_u32 v32, v205, 2, s91
	v_lshl_add_u32 v33, v204, 2, s91
	ds_read_b32 v18, v18 offset:512
	ds_read_b32 v19, v19 offset:512
	ds_read_b32 v20, v20 offset:512
	ds_read_b32 v21, v21 offset:512
	ds_read_b32 v22, v22 offset:512
	ds_read_b32 v23, v23 offset:512
	ds_read_b32 v24, v24 offset:512
	ds_read_b32 v25, v25 offset:512
	ds_read_b32 v196, v26 offset:512
	ds_read_b32 v197, v27 offset:512
	ds_read_b32 v198, v28 offset:512
	ds_read_b32 v199, v29 offset:512
	ds_read_b32 v200, v30 offset:512
	ds_read_b32 v201, v31 offset:512
	ds_read_b32 v202, v32 offset:512
	ds_read_b32 v203, v33 offset:512
	s_waitcnt lgkmcnt(8)
	v_fma_f32 v32, v146, s36, v24
	v_fma_f32 v33, v147, s36, v25
	v_fma_f32 v30, v144, s36, v22
	v_fma_f32 v31, v145, s36, v23
	v_fma_f32 v28, v142, s36, v20
	v_fma_f32 v29, v143, s36, v21
	v_fma_f32 v26, v140, s36, v18
	v_fma_f32 v27, v141, s36, v19
	s_waitcnt lgkmcnt(0)
	v_fma_f32 v24, v138, s36, v202
	v_fma_f32 v25, v139, s36, v203
	v_fma_f32 v22, v136, s36, v200
	v_fma_f32 v23, v137, s36, v201
	v_fma_f32 v20, v134, s36, v198
	v_fma_f32 v21, v135, s36, v199
	v_fma_f32 v18, v132, s36, v196
	v_fma_f32 v19, v133, s36, v197
.LBB0_683:
	s_andn2_saveexec_b64 s[2:3], s[2:3]
	s_nop 3
	v_fma_f32 v32, v146, s36, v174
	v_fma_f32 v33, v147, s36, v174
	v_fma_f32 v28, v142, s36, v174
	v_fma_f32 v29, v143, s36, v174
	v_fma_f32 v24, v138, s36, v174
	v_fma_f32 v25, v139, s36, v174
	v_fma_f32 v20, v134, s36, v174
	v_fma_f32 v21, v135, s36, v174
	v_fma_f32 v30, v144, s36, v174
	v_fma_f32 v31, v145, s36, v174
	v_fma_f32 v26, v140, s36, v174
	v_fma_f32 v27, v141, s36, v174
	v_fma_f32 v22, v136, s36, v174
	v_fma_f32 v23, v137, s36, v174
	v_fma_f32 v18, v132, s36, v174
	v_fma_f32 v19, v133, s36, v174
	s_or_b64 exec, exec, s[2:3]
	v_max_f32_e32 v132, v19, v19
	v_max_f32_e32 v133, v18, v18
	v_max_f32_e32 v132, v133, v132
	v_max3_f32 v132, v132, v20, v21
	v_max3_f32 v132, v132, v22, v23
	v_max3_f32 v132, v132, v24, v25
	v_max3_f32 v132, v132, v26, v27
	v_max3_f32 v132, v132, v28, v29
	v_max3_f32 v132, v132, v30, v31
	v_max3_f32 v132, v132, v32, v33
	ds_bpermute_b32 v133, v35, v132
	s_waitcnt lgkmcnt(0)
	v_max_f32_e32 v133, v133, v133
	v_max_f32_e32 v132, v132, v133
	ds_bpermute_b32 v133, v149, v132
	s_add_i32 s2, s49, -1
	s_cmp_ge_i32 s2, s30
	s_cbranch_scc1 .LBB0_688
	s_xor_b32 s2, s50, 1
	v_lshl_add_u32 v134, s2, 14, v178
	s_waitcnt vmcnt(3)
	ds_write_b128 v134, v[72:75]
	s_waitcnt vmcnt(2)
	ds_write_b128 v134, v[80:83] offset:512
	v_lshl_add_u32 v134, s2, 7, v154
	v_mad_u64_u32 v[134:135], s[2:3], v134, s92, v[152:153]
	s_cmp_ge_i32 s49, s30
	s_waitcnt vmcnt(1)
	ds_write_b16 v134, v84 offset:34816
	ds_write_b16_d16_hi v134, v84 offset:34960
	ds_write_b16 v134, v85 offset:35104
	ds_write_b16_d16_hi v134, v85 offset:35248
	ds_write_b16 v134, v86 offset:35392
	ds_write_b16_d16_hi v134, v86 offset:35536
	ds_write_b16 v134, v87 offset:35680
	ds_write_b16_d16_hi v134, v87 offset:35824
	s_waitcnt vmcnt(0)
	ds_write_b16 v134, v92 offset:35968
	ds_write_b16_d16_hi v134, v92 offset:36112
	ds_write_b16 v134, v93 offset:36256
	ds_write_b16_d16_hi v134, v93 offset:36400
	ds_write_b16 v134, v94 offset:36544
	ds_write_b16_d16_hi v134, v94 offset:36688
	ds_write_b16 v134, v95 offset:36832
	ds_write_b16_d16_hi v134, v95 offset:36976
	s_cbranch_scc1 .LBB0_688
	v_add_co_u32_e32 v72, vcc, 0xfffc2000, v170
	s_nop 1
	v_addc_co_u32_e32 v73, vcc, -1, v171, vcc
	global_load_dwordx4 v[72:75], v[72:73], off
	s_nop 0
	global_load_dwordx4 v[80:83], v[170:171], off
	global_load_dwordx4 v[84:87], v[172:173], off offset:-16
	global_load_dwordx4 v[92:95], v[172:173], off
.LBB0_688:
	s_waitcnt lgkmcnt(0)
	v_max3_f32 v133, v193, v132, v133
	v_sub_f32_e32 v18, v18, v133
	v_exp_f32_e32 v134, v18
	v_sub_f32_e32 v19, v19, v133
	v_exp_f32_e32 v19, v19
	v_sub_f32_e32 v20, v20, v133
	v_exp_f32_e32 v20, v20
	v_sub_f32_e32 v21, v21, v133
	v_exp_f32_e32 v21, v21
	v_sub_f32_e32 v22, v22, v133
	v_add_f32_e32 v132, 0, v134
	v_exp_f32_e32 v135, v22
	v_sub_f32_e32 v23, v23, v133
	v_add_f32_e32 v22, v19, v132
	v_exp_f32_e32 v136, v23
	v_sub_f32_e32 v23, v24, v133
	v_add_f32_e32 v22, v20, v22
	v_exp_f32_e32 v137, v23
	v_sub_f32_e32 v23, v25, v133
	v_add_f32_e32 v22, v21, v22
	v_exp_f32_e32 v138, v23
	v_sub_f32_e32 v23, v26, v133
	v_add_f32_e32 v22, v135, v22
	v_exp_f32_e32 v139, v23
	v_sub_f32_e32 v23, v27, v133
	v_add_f32_e32 v22, v136, v22
	v_exp_f32_e32 v140, v23
	v_sub_f32_e32 v23, v28, v133
	v_add_f32_e32 v22, v137, v22
	v_exp_f32_e32 v141, v23
	v_sub_f32_e32 v23, v29, v133
	v_add_f32_e32 v22, v138, v22
	v_exp_f32_e32 v142, v23
	v_sub_f32_e32 v23, v30, v133
	v_add_f32_e32 v22, v139, v22
	v_exp_f32_e32 v143, v23
	v_sub_f32_e32 v23, v31, v133
	v_add_f32_e32 v22, v140, v22
	v_exp_f32_e32 v144, v23
	v_sub_f32_e32 v23, v32, v133
	v_sub_f32_e32 v18, v193, v133
	v_add_f32_e32 v22, v141, v22
	v_exp_f32_e32 v145, v23
	v_sub_f32_e32 v23, v33, v133
	v_add_f32_e32 v22, v142, v22
	v_exp_f32_e32 v146, v23
	v_exp_f32_e32 v18, v18
	v_add_f32_e32 v22, v143, v22
	v_add_f32_e32 v22, v144, v22
	v_add_f32_e32 v22, v145, v22
	v_add_f32_e32 v132, v146, v22
	v_mul_f32_e32 v22, v100, v18
	v_mul_f32_e32 v23, v101, v18
	v_cvt_pk_f16_f32 v100, v134, v19
	v_max3_f32 v134, v191, v194, v195
	v_sub_f32_e32 v2, v2, v134
	v_mul_f32_e32 v30, v108, v18
	v_mul_f32_e32 v31, v109, v18
	v_exp_f32_e32 v108, v2
	v_sub_f32_e32 v3, v3, v134
	v_exp_f32_e32 v3, v3
	v_sub_f32_e32 v4, v4, v134
	v_mul_f32_e32 v32, v110, v18
	v_mul_f32_e32 v33, v111, v18
	v_exp_f32_e32 v110, v4
	v_sub_f32_e32 v4, v5, v134
	v_exp_f32_e32 v111, v4
	v_sub_f32_e32 v4, v6, v134
	v_mul_f32_e32 v26, v128, v18
	v_mul_f32_e32 v27, v129, v18
	v_add_f32_e32 v109, 0, v108
	v_exp_f32_e32 v128, v4
	v_sub_f32_e32 v5, v7, v134
	v_add_f32_e32 v4, v3, v109
	v_exp_f32_e32 v109, v5
	v_sub_f32_e32 v5, v8, v134
	v_add_f32_e32 v4, v110, v4
	v_exp_f32_e32 v129, v5
	v_sub_f32_e32 v5, v9, v134
	v_mul_f32_e32 v28, v130, v18
	v_mul_f32_e32 v29, v131, v18
	v_add_f32_e32 v4, v111, v4
	v_exp_f32_e32 v130, v5
	v_sub_f32_e32 v5, v10, v134
	v_add_f32_e32 v4, v128, v4
	v_exp_f32_e32 v131, v5
	v_sub_f32_e32 v5, v11, v134
	v_mul_f32_e32 v24, v102, v18
	v_mul_f32_e32 v25, v103, v18
	v_cvt_pk_f16_f32 v102, v135, v136
	v_add_f32_e32 v4, v109, v4
	v_exp_f32_e32 v135, v5
	v_sub_f32_e32 v5, v12, v134
	v_add_f32_e32 v4, v129, v4
	v_exp_f32_e32 v136, v5
	v_sub_f32_e32 v5, v13, v134
	v_cvt_pk_f16_f32 v103, v137, v138
	v_add_f32_e32 v4, v130, v4
	v_exp_f32_e32 v137, v5
	v_sub_f32_e32 v5, v14, v134
	v_add_f32_e32 v4, v131, v4
	v_exp_f32_e32 v138, v5
	v_sub_f32_e32 v5, v15, v134
	v_fmac_f32_e32 v132, v192, v18
	v_mul_f32_e32 v126, v126, v18
	v_mul_f32_e32 v127, v127, v18
	v_mul_f32_e32 v124, v124, v18
	v_mul_f32_e32 v125, v125, v18
	v_mul_f32_e32 v122, v122, v18
	v_mul_f32_e32 v123, v123, v18
	v_mul_f32_e32 v120, v120, v18
	v_mul_f32_e32 v121, v121, v18
	v_mul_f32_e32 v118, v118, v18
	v_mul_f32_e32 v119, v119, v18
	v_mul_f32_e32 v116, v116, v18
	v_mul_f32_e32 v117, v117, v18
	v_mul_f32_e32 v114, v114, v18
	v_mul_f32_e32 v115, v115, v18
	v_mul_f32_e32 v112, v112, v18
	v_mul_f32_e32 v113, v113, v18
	v_mul_f32_e32 v106, v106, v18
	v_mul_f32_e32 v107, v107, v18
	v_mul_f32_e32 v104, v104, v18
	v_mul_f32_e32 v105, v105, v18
	v_cvt_pk_f16_f32 v18, v139, v140
	v_add_f32_e32 v4, v135, v4
	v_exp_f32_e32 v139, v5
	v_sub_f32_e32 v5, v16, v134
	v_add_f32_e32 v4, v136, v4
	v_exp_f32_e32 v140, v5
	v_sub_f32_e32 v5, v17, v134
	v_sub_f32_e32 v2, v191, v134
	v_add_f32_e32 v4, v137, v4
	v_exp_f32_e32 v17, v5
	v_add_f32_e32 v4, v138, v4
	v_exp_f32_e32 v16, v2
	v_add_f32_e32 v2, v139, v4
	v_add_f32_e32 v2, v140, v2
	v_add_f32_e32 v2, v17, v2
	v_cvt_pk_f16_f32 v101, v20, v21
	v_fmac_f32_e32 v2, v190, v16
	v_mul_f32_e32 v10, v78, v16
	v_mul_f32_e32 v11, v79, v16
	v_mul_f32_e32 v8, v76, v16
	v_mul_f32_e32 v9, v77, v16
	v_mul_f32_e32 v14, v70, v16
	v_mul_f32_e32 v15, v71, v16
	v_mul_f32_e32 v12, v68, v16
	v_mul_f32_e32 v13, v69, v16
	v_mul_f32_e32 v66, v66, v16
	v_mul_f32_e32 v67, v67, v16
	v_mul_f32_e32 v64, v64, v16
	v_mul_f32_e32 v65, v65, v16
	v_mul_f32_e32 v62, v62, v16
	v_mul_f32_e32 v63, v63, v16
	v_mul_f32_e32 v60, v60, v16
	v_mul_f32_e32 v61, v61, v16
	v_mul_f32_e32 v58, v58, v16
	v_mul_f32_e32 v59, v59, v16
	v_mul_f32_e32 v56, v56, v16
	v_mul_f32_e32 v57, v57, v16
	v_mul_f32_e32 v54, v54, v16
	v_mul_f32_e32 v55, v55, v16
	v_mul_f32_e32 v52, v52, v16
	v_mul_f32_e32 v53, v53, v16
	v_mul_f32_e32 v70, v98, v16
	v_mul_f32_e32 v71, v99, v16
	v_mul_f32_e32 v68, v96, v16
	v_mul_f32_e32 v69, v97, v16
	v_cvt_pk_f16_f32 v76, v108, v3
	v_cvt_pk_f16_f32 v77, v110, v111
	v_cvt_pk_f16_f32 v78, v128, v109
	v_cvt_pk_f16_f32 v79, v129, v130
	v_cvt_pk_f16_f32 v96, v131, v135
	v_cvt_pk_f16_f32 v97, v136, v137
	v_cvt_pk_f16_f32 v98, v138, v139
	v_cvt_pk_f16_f32 v99, v140, v17
	v_cvt_pk_f16_f32 v19, v141, v142
	v_cvt_pk_f16_f32 v20, v143, v144
	v_cvt_pk_f16_f32 v21, v145, v146
	v_mul_f32_e32 v6, v90, v16
	v_mul_f32_e32 v7, v91, v16
	v_mul_f32_e32 v4, v88, v16
	v_mul_f32_e32 v5, v89, v16
	v_lshl_or_b32 v3, s50, 7, v151
	v_mad_u32_u24 v3, v3, s92, v177
	v_add_u32_e32 v16, 0x8800, v3
	ds_read_b64 v[88:89], v16
	ds_read_b64 v[90:91], v16 offset:32
	v_add_u32_e32 v17, 0x9000, v3
	s_waitcnt lgkmcnt(0)
	v_mfma_f32_16x16x32_f16 v[4:7], v[88:91], v[76:79], v[4:7]
	v_mfma_f32_16x16x32_f16 v[108:111], v[88:91], v[100:103], v[124:127]
	ds_read_b64 v[88:89], v17 offset:256
	ds_read_b64 v[90:91], v17 offset:288
	s_waitcnt lgkmcnt(0)
	v_mfma_f32_16x16x32_f16 v[120:123], v[88:91], v[100:103], v[120:123]
	v_mfma_f32_16x16x32_f16 v[8:11], v[88:91], v[76:79], v[8:11]
	v_add_u32_e32 v135, 0x9800, v3
	ds_read_b64 v[88:89], v135 offset:512
	ds_read_b64 v[90:91], v135 offset:544
	v_add_u32_e32 v136, 0xa000, v3
	s_waitcnt lgkmcnt(0)
	v_mfma_f32_16x16x32_f16 v[12:15], v[88:91], v[76:79], v[12:15]
	v_mfma_f32_16x16x32_f16 v[116:119], v[88:91], v[100:103], v[116:119]
	ds_read_b64 v[88:89], v136 offset:768
	ds_read_b64 v[90:91], v136 offset:800
	s_waitcnt lgkmcnt(0)
	v_mfma_f32_16x16x32_f16 v[64:67], v[88:91], v[76:79], v[64:67]
	v_mfma_f32_16x16x32_f16 v[112:115], v[88:91], v[100:103], v[112:115]
	v_add_u32_e32 v137, 0xa800, v3
	ds_read_b64 v[88:89], v137 offset:1024
	ds_read_b64 v[90:91], v137 offset:1056
	v_add_u32_e32 v138, 0xb000, v3
	s_waitcnt lgkmcnt(0)
	v_mfma_f32_16x16x32_f16 v[60:63], v[88:91], v[76:79], v[60:63]
	v_mfma_f32_16x16x32_f16 v[30:33], v[88:91], v[100:103], v[30:33]
	ds_read_b64 v[88:89], v138 offset:1280
	ds_read_b64 v[90:91], v138 offset:1312
	s_waitcnt lgkmcnt(0)
	v_mfma_f32_16x16x32_f16 v[56:59], v[88:91], v[76:79], v[56:59]
	v_mfma_f32_16x16x32_f16 v[104:107], v[88:91], v[100:103], v[104:107]
	v_add_u32_e32 v139, 0xb800, v3
	ds_read_b64 v[88:89], v139 offset:1536
	ds_read_b64 v[90:91], v139 offset:1568
	v_add_u32_e32 v3, 0xc000, v3
	s_waitcnt lgkmcnt(0)
	v_mfma_f32_16x16x32_f16 v[52:55], v[88:91], v[76:79], v[52:55]
	v_mfma_f32_16x16x32_f16 v[22:25], v[88:91], v[100:103], v[22:25]
	ds_read_b64 v[88:89], v3 offset:1792
	ds_read_b64 v[90:91], v3 offset:1824
	s_waitcnt lgkmcnt(0)
	v_mfma_f32_16x16x32_f16 v[128:131], v[88:91], v[76:79], v[68:71]
	v_mfma_f32_16x16x32_f16 v[26:29], v[88:91], v[100:103], v[26:29]
	s_nop 1
	ds_read_b64 v[68:69], v16 offset:64
	ds_read_b64 v[70:71], v16 offset:96
	s_waitcnt lgkmcnt(0)
	v_mfma_f32_16x16x32_f16 v[88:91], v[68:71], v[96:99], v[4:7]
	s_nop 2
	ds_read_b64 v[4:5], v17 offset:320
	ds_read_b64 v[6:7], v17 offset:352
	v_mfma_f32_16x16x32_f16 v[124:127], v[68:71], v[18:21], v[108:111]
	s_waitcnt lgkmcnt(0)
	v_mfma_f32_16x16x32_f16 v[76:79], v[4:7], v[96:99], v[8:11]
	v_mfma_f32_16x16x32_f16 v[120:123], v[4:7], v[18:21], v[120:123]
	ds_read_b64 v[4:5], v135 offset:576
	ds_read_b64 v[6:7], v135 offset:608
	s_waitcnt lgkmcnt(0)
	v_mfma_f32_16x16x32_f16 v[68:71], v[4:7], v[96:99], v[12:15]
	v_mfma_f32_16x16x32_f16 v[116:119], v[4:7], v[18:21], v[116:119]
	ds_read_b64 v[4:5], v136 offset:832
	ds_read_b64 v[6:7], v136 offset:864
	s_waitcnt lgkmcnt(0)
	v_mfma_f32_16x16x32_f16 v[64:67], v[4:7], v[96:99], v[64:67]
	v_mfma_f32_16x16x32_f16 v[112:115], v[4:7], v[18:21], v[112:115]
	ds_read_b64 v[4:5], v137 offset:1088
	ds_read_b64 v[6:7], v137 offset:1120
	s_waitcnt lgkmcnt(0)
	v_mfma_f32_16x16x32_f16 v[60:63], v[4:7], v[96:99], v[60:63]
	v_mfma_f32_16x16x32_f16 v[108:111], v[4:7], v[18:21], v[30:33]
	ds_read_b64 v[4:5], v138 offset:1344
	ds_read_b64 v[6:7], v138 offset:1376
	s_waitcnt lgkmcnt(0)
	v_mfma_f32_16x16x32_f16 v[56:59], v[4:7], v[96:99], v[56:59]
	v_mfma_f32_16x16x32_f16 v[104:107], v[4:7], v[18:21], v[104:107]
	ds_read_b64 v[4:5], v139 offset:1600
	ds_read_b64 v[6:7], v139 offset:1632
	s_waitcnt lgkmcnt(0)
	v_mfma_f32_16x16x32_f16 v[52:55], v[4:7], v[96:99], v[52:55]
	v_mfma_f32_16x16x32_f16 v[100:103], v[4:7], v[18:21], v[22:25]
	ds_read_b64 v[4:5], v3 offset:1856
	ds_read_b64 v[6:7], v3 offset:1888
	s_waitcnt lgkmcnt(0)
	v_mfma_f32_16x16x32_f16 v[96:99], v[4:7], v[96:99], v[128:131]
	v_mfma_f32_16x16x32_f16 v[128:131], v[4:7], v[18:21], v[26:29]
	s_add_i32 s49, s49, 1
	s_add_i32 s24, s24, 64
	s_add_i32 s2, s31, s49
	v_lshl_add_u64 v[172:173], v[172:173], 0, s[20:21]
	v_lshl_add_u64 v[170:171], v[170:171], 0, s[20:21]
	s_cmp_eq_u32 s2, 2
	v_subrev_u32_e32 v167, 64, v167
	s_barrier
	s_cbranch_scc1 .LBB0_691
	v_mov_b32_e32 v193, v133
	v_mov_b32_e32 v191, v134
	v_mov_b32_e32 v192, v132
	v_mov_b32_e32 v190, v2
	s_branch .LBB0_677

.LBB0_736:
	s_abs_i32 s45, s62
	s_mul_hi_u32 s46, s45, s61
	s_mul_i32 s47, s46, s59
	s_sub_i32 s45, s45, s47
	s_ashr_i32 s44, s62, 31
	s_add_i32 s47, s46, 1
	s_sub_i32 s48, s45, s59
	s_cmp_ge_u32 s45, s59
	s_cselect_b32 s46, s47, s46
	s_cselect_b32 s45, s48, s45
	s_add_i32 s47, s46, 1
	s_cmp_ge_u32 s45, s59
	s_cselect_b32 s45, s47, s46
	s_xor_b32 s45, s45, s44
	s_sub_i32 s45, s45, s44
	s_lshl_b32 s44, s45, 6
	s_mul_i32 s45, s45, s59
	s_sub_i32 s45, s62, s45
	s_lshl_b32 s46, s45, 6
	s_ashr_i32 s47, s46, 31
	v_mov_b32_e32 v10, v1
	s_lshl_b64 s[48:49], s[46:47], 2
	s_waitcnt lgkmcnt(0)
	s_add_u32 s48, s40, s48
	v_lshlrev_b32_e32 v2, 4, v10
	v_ashrrev_i32_e32 v11, 4, v10
	s_addc_u32 s49, s41, s49
	v_and_b32_e32 v6, 0xf0, v2
	v_mov_b32_e32 v7, v34
	v_lshl_add_u64 v[8:9], s[48:49], 0, v[6:7]
	v_add_u32_e32 v7, s44, v11
	v_mad_u64_u32 v[2:3], s[48:49], v7, s24, 0
	v_ashrrev_i32_e32 v5, 31, v7
	v_mov_b32_e32 v4, v3
	v_mad_u64_u32 v[4:5], s[48:49], v5, s24, v[4:5]
	v_mov_b32_e32 v3, v4
	v_lshl_add_u64 v[2:3], v[2:3], 2, v[8:9]
	global_load_dwordx4 v[2:5], v[2:3], off nt
	v_add_u32_e32 v246, 32, v7
	v_ashrrev_i32_e32 v249, 31, v246
	v_mad_u64_u32 v[246:247], s[48:49], v246, s24, 0
	v_mov_b32_e32 v248, v247
	v_mad_u64_u32 v[248:249], s[48:49], v249, s24, v[248:249]
	v_mov_b32_e32 v247, v248
	v_lshl_add_u64 v[246:247], v[246:247], 2, v[8:9]
	global_load_dwordx4 v[246:249], v[246:247], off nt
	v_mul_lo_u32 v11, v11, s86
	v_add3_u32 v6, 0, v6, v11
	v_ashrrev_i32_e32 v11, 3, v10
	s_ashr_i32 s45, s44, 31
	s_waitcnt vmcnt(1)
	ds_write2_b32 v6, v2, v3 offset1:1
	ds_write2_b32 v6, v4, v5 offset0:2 offset1:3
	v_add_u32_e32 v7, 0x2080, v6
	s_waitcnt vmcnt(0)
	ds_write2_b32 v7, v246, v247 offset1:1
	v_add_u32_e32 v2, 0x2088, v6
	ds_write2_b32 v2, v248, v249 offset1:1
	v_lshlrev_b32_e32 v2, 3, v10
	v_and_b32_e32 v10, 56, v2
	v_lshlrev_b32_e32 v2, 2, v11
	v_mul_u32_u24_e32 v3, 0x104, v10
	v_add3_u32 v6, 0, v2, v3
	s_waitcnt lgkmcnt(0)
	s_barrier
	ds_read2_b32 v[2:3], v6 offset1:65
	ds_read2_b32 v[4:5], v6 offset0:130 offset1:195
	v_add_u32_e32 v8, 0x400, v6
	ds_read2_b32 v[6:7], v8 offset0:4 offset1:69
	ds_read2_b32 v[8:9], v8 offset0:134 offset1:199
	s_waitcnt lgkmcnt(3)
	v_cvt_pk_f16_f32 v2, v2, v3
	s_waitcnt lgkmcnt(2)
	v_cvt_pk_f16_f32 v3, v4, v5
	s_waitcnt lgkmcnt(1)
	v_cvt_pk_f16_f32 v4, v6, v7
	v_add_u32_e32 v6, s46, v11
	s_waitcnt lgkmcnt(0)
	v_cvt_pk_f16_f32 v5, v8, v9
	v_ashrrev_i32_e32 v9, 31, v6
	v_mad_u64_u32 v[6:7], s[46:47], v6, s58, 0
	v_mov_b32_e32 v8, v7
	v_mad_u64_u32 v[8:9], s[46:47], v9, s58, v[8:9]
	v_mov_b32_e32 v7, v8
	v_lshl_add_u64 v[6:7], v[6:7], 1, s[42:43]
	v_lshl_add_u64 v[6:7], s[44:45], 1, v[6:7]
	v_lshlrev_b32_e32 v8, 1, v10
	v_mov_b32_e32 v9, v34
	v_lshl_add_u64 v[6:7], v[6:7], 0, v[8:9]
	global_store_dwordx4 v[6:7], v[2:5], off
	s_barrier
	s_load_dword s44, s[72:73], 0x10
	s_waitcnt lgkmcnt(0)
	s_lshr_b32 s44, s44, 16
	s_cmp_lg_u32 s44, 0
	s_cselect_b64 s[44:45], -1, 0
	s_cmp_lg_u64 s[44:45], 0
	s_addc_u32 s62, s62, s74
	s_cmp_ge_i32 s62, s60
	s_cbranch_scc0 .LBB0_736
	s_branch .LBB0_703
